# attention: QK-stage waits no longer drain this step's K/V prefetch (vmcnt dropped, Q covered by vmcnt(2)); step-start K/V waits count the previous step's loads (vmcnt(3)/(2))
# speedup vs baseline: 1.0076x; 1.0076x over previous
; #define LAS __attribute__((address_space(3)))
; __device__ __forceinline__ void attn_run_coop(int nq, int p, int hd, int res, int x0, const bf16_t* __restrict__ AQ, const bf16_t* __restrict__ AK, const bf16_t* __restrict__ AV, bf16_t* __restrict__ OP, float* __restrict__ LSE, ...
;     const int lg = (p == 0) ? 0 : (p == 1) ? 2 : 4, dl = 1 << lg;
;     const int r = lane & 31, h = lane >> 5, lkey = lane >> 4, lch = lane & 15, rr = r - 4 * h, myrow = 4 * w + lkey;
;     LAS bf16_t* const K0 = lbase; LAS bf16_t* const V0 = lbase + 4352; LAS bf16_t* const K1 = lbase + 8704; LAS bf16_t* const V1 = lbase + 8704 + 4352;
;     const unsigned lanepart = (unsigned)(((4 * (lane >> 5) + ((lane & 15) >> 2)) * 136 + 16 * ((lane >> 4) & 1) + 4 * (lane & 3)) * 2);
;     const unsigned vaddr0 = (unsigned)(size_t)V0 + lanepart, vaddr1 = (unsigned)(size_t)V1 + lanepart;
;     u32x4 kA = (u32x4){0u, 0u, 0u, 0u}, vA = kA, kB = kA, vB = kA;
;     bf16x8 qf[8]; f32x16 o[4]; float mrun = -INFINITY, lrun = 0.f; size_t qtok = 0;
; #pragma unroll
;     for (int j = 0; j < 8; ++j) qf[j] = (bf16x8){0, 0, 0, 0, 0, 0, 0, 0};
; #pragma unroll
;     for (int dt = 0; dt < 4; ++dt)
; #pragma unroll
;         for (int i = 0; i < 16; ++i) o[dt][i] = 0.f;
;     if (ATT_TILE_VALID(0)) { const unsigned vo = ATT_VOFF(0); kA = *(const u32x4*)((const char*)AK + vo); vA = *(const u32x4*)((const char*)AV + vo); }
;     if (ATT_TILE_VALID(1)) { const unsigned vo = ATT_VOFF(1); kB = *(const u32x4*)((const char*)AK + vo); vB = *(const u32x4*)((const char*)AV + vo); }
;     ATT_BOOK(-1);
;     if (ATT_TILE_VALID(0)) { *(LAS u32x4*)(K0 + myrow * 136 + 8 * lch) = kA; *(LAS u32x4*)(V0 + myrow * 136 + 8 * lch) = vA; }
;     if (ATT_TILE_VALID(2)) { const unsigned vo = ATT_VOFF(2); kA = *(const u32x4*)((const char*)AK + vo); vA = *(const u32x4*)((const char*)AV + vo); }
;     asm volatile("s_waitcnt lgkmcnt(0)" ::: "memory"); __builtin_amdgcn_s_barrier(); asm volatile("" ::: "memory");
.LBB0_506:
	v_lshlrev_b32_e32 v168, 2, v8
	s_waitcnt vmcnt(0)
	v_lshrrev_b32_e32 v0, 2, v181
	v_or_b32_e32 v0, v168, v0
	v_and_b32_e32 v1, 16, v209
	v_lshlrev_b32_e32 v2, 2, v209
	v_mul_u32_u24_e32 v0, 0x88, v0
	v_and_or_b32 v1, v2, 12, v1
	v_add_lshl_u32 v0, v1, v0, 1
	s_add_i32 s0, 0, 0x2200
	v_add_u32_e32 v176, s0, v0
	v_sub_u32_e32 v1, v180, v168
	s_add_i32 s0, 0, 0x6600
	v_add_u32_e32 v177, s0, v0
	v_readlane_b32 s0, v245, 23
	v_cmp_lt_i32_e64 s[36:37], 0, v1
	v_readlane_b32 s1, v245, 24
	s_lshl_b32 s79, s73, 7
	v_writelane_b32 v245, s36, 47
	s_lshl_b32 s44, s73, 8
	s_mov_b32 s75, 0
	v_writelane_b32 v245, s37, 48
	v_cmp_lt_i32_e64 s[36:37], 1, v1
	s_add_u32 s0, s0, s44
	s_addc_u32 s1, s1, 0
	v_writelane_b32 v245, s36, 53
	s_movk_i32 s4, 0x110
	v_or_b32_e32 v183, s3, v9
	v_writelane_b32 v245, s37, 54
	v_cmp_lt_i32_e64 s[36:37], 2, v1
	v_mul_lo_u32 v0, v182, s4
	v_add3_u32 v178, 0, v0, v169
	v_writelane_b32 v245, s36, 55
	v_mov_b32_e32 v0, 0
	v_lshlrev_b32_e32 v172, 3, v8
	v_writelane_b32 v245, s37, 56
	v_cmp_lt_i32_e64 s[36:37], 3, v1
	v_mov_b32_e32 v173, v0
	v_mov_b32_e32 v165, v0
	v_writelane_b32 v245, s36, 57
	s_waitcnt lgkmcnt(0)
	s_barrier
	v_lshl_add_u64 v[166:167], s[0:1], 0, v[164:165]
	v_writelane_b32 v245, s37, 58
	v_cmp_lt_i32_e64 s[36:37], 8, v1
	v_mad_u32_u24 v165, v180, s4, 0
	v_cmp_gt_i32_e64 s[0:1], 0, v1
	v_writelane_b32 v245, s36, 59
	v_cmp_gt_i32_e64 s[4:5], 1, v1
	v_cmp_gt_i32_e64 s[6:7], 2, v1
	v_writelane_b32 v245, s37, 60
	v_cmp_lt_i32_e64 s[36:37], 9, v1
	v_cmp_gt_i32_e64 s[8:9], 3, v1
	v_cmp_gt_i32_e64 s[10:11], 8, v1
	v_writelane_b32 v245, s36, 61
	v_cmp_gt_i32_e64 s[12:13], 9, v1
	v_cmp_gt_i32_e64 s[14:15], 10, v1
	v_writelane_b32 v245, s37, 62
	v_cmp_lt_i32_e64 s[36:37], 10, v1
	v_cmp_gt_i32_e64 s[16:17], 11, v1
	v_cmp_gt_i32_e64 s[18:19], 16, v1
	v_writelane_b32 v245, s36, 63
	v_cmp_gt_i32_e64 s[20:21], 17, v1
	v_cmp_gt_i32_e64 s[22:23], 18, v1
	v_writelane_b32 v244, s37, 0
	v_cmp_lt_i32_e64 s[36:37], 11, v1
	v_cmp_gt_i32_e64 s[24:25], 19, v1
	v_cmp_gt_i32_e64 s[26:27], 24, v1
	v_writelane_b32 v244, s36, 1
	v_cmp_gt_i32_e64 s[28:29], 25, v1
	v_cmp_gt_i32_e64 s[30:31], 26, v1
	v_writelane_b32 v244, s37, 2
	s_lshl_b64 s[36:37], s[74:75], 25
	s_add_u32 s3, s90, s36
	s_addc_u32 s37, s91, s37
	s_add_u32 s36, s3, s44
	s_addc_u32 s37, s37, 0
	v_lshl_add_u64 v[2:3], s[36:37], 0, v[172:173]
	s_mov_b64 s[36:37], 0x19700000
	v_lshl_add_u64 v[174:175], v[2:3], 0, s[36:37]
	s_lshl_b64 s[36:37], s[74:75], 19
	s_add_u32 s3, s90, s36
	s_addc_u32 s36, s91, s37
	s_lshl_b32 s37, s73, 14
	v_writelane_b32 v244, s37, 3
	s_lshl_b32 s37, s73, 16
	s_add_u32 s3, s3, s37
	s_addc_u32 s36, s36, 0
	s_add_u32 s50, s3, 0x4500000
	s_addc_u32 s51, s36, 0
	s_add_i32 s2, s2, s33
	v_cmp_gt_i32_e64 s[34:35], 27, v1
	v_cmp_lt_i32_e64 s[52:53], 16, v1
	v_cmp_lt_i32_e64 s[54:55], 17, v1
	v_cmp_lt_i32_e64 s[56:57], 18, v1
	v_cmp_lt_i32_e64 s[58:59], 19, v1
	v_cmp_lt_i32_e64 s[60:61], 24, v1
	v_cmp_lt_i32_e64 s[62:63], 25, v1
	v_cmp_lt_i32_e64 s[64:65], 26, v1
	v_cmp_lt_i32_e64 s[66:67], 27, v1
	v_add_u32_e32 v1, s2, v179
	v_mov_b32_e32 v14, v0
	v_mov_b32_e32 v15, v0
	v_add_u32_e32 v173, 0x200000, v1
	v_mov_b32_e32 v1, v0
	v_mov_b32_e32 v2, v0
	v_mov_b32_e32 v3, v0
	v_mov_b32_e32 v4, v0
	v_mov_b32_e32 v5, v0
	v_mov_b32_e32 v6, v0
	v_mov_b32_e32 v7, v0
	v_mov_b32_e32 v8, v0
	v_mov_b32_e32 v9, v0
	v_mov_b32_e32 v10, v0
	v_mov_b32_e32 v11, v0
	v_mov_b32_e32 v12, v0
	v_mov_b32_e32 v13, v0
	v_mov_b64_e32 v[30:31], v[14:15]
	v_mov_b64_e32 v[46:47], v[14:15]
	v_mov_b64_e32 v[62:63], v[14:15]
	v_mov_b64_e32 v[78:79], v[14:15]
	v_cmp_gt_u32_e64 s[68:69], 32, v208
	s_sub_i32 s3, 0, s78
	v_add3_u32 v184, s33, v180, 32
	v_mov_b32_e32 v185, 0xff800000
	s_mov_b32 s74, 0x3e0293ee
	v_mov_b64_e32 v[28:29], v[12:13]
	v_mov_b64_e32 v[26:27], v[10:11]
	v_mov_b64_e32 v[24:25], v[8:9]
	v_mov_b64_e32 v[22:23], v[6:7]
	v_mov_b64_e32 v[20:21], v[4:5]
	v_mov_b64_e32 v[18:19], v[2:3]
	v_mov_b64_e32 v[16:17], v[0:1]
	v_mov_b64_e32 v[44:45], v[12:13]
	v_mov_b64_e32 v[42:43], v[10:11]
	v_mov_b64_e32 v[40:41], v[8:9]
	v_mov_b64_e32 v[38:39], v[6:7]
	v_mov_b64_e32 v[36:37], v[4:5]
	v_mov_b64_e32 v[34:35], v[2:3]
	v_mov_b64_e32 v[32:33], v[0:1]
	v_mov_b64_e32 v[60:61], v[12:13]
	v_mov_b64_e32 v[58:59], v[10:11]
	v_mov_b64_e32 v[56:57], v[8:9]
	v_mov_b64_e32 v[54:55], v[6:7]
	v_mov_b64_e32 v[52:53], v[4:5]
	v_mov_b64_e32 v[50:51], v[2:3]
	v_mov_b64_e32 v[48:49], v[0:1]
	v_mov_b64_e32 v[76:77], v[12:13]
	v_mov_b64_e32 v[74:75], v[10:11]
	v_mov_b64_e32 v[72:73], v[8:9]
	v_mov_b64_e32 v[70:71], v[6:7]
	v_mov_b64_e32 v[68:69], v[4:5]
	v_mov_b64_e32 v[66:67], v[2:3]
	v_mov_b64_e32 v[64:65], v[0:1]
	v_mov_b32_e32 v186, 0
	v_mov_b32_e32 v187, 0xff800000
	s_mov_b32 s99, 0
	s_branch .LBB0_510

.LBB0_510:
	s_add_i32 s46, s42, s75
	s_and_b32 s2, s46, 0x7fffffc
	s_cmp_eq_u32 s2, 0
	s_cselect_b64 s[36:37], -1, 0
	s_cmp_lg_u32 s2, 0
	s_cselect_b64 s[38:39], -1, 0
	s_and_b64 vcc, exec, s[36:37]
	s_cbranch_vccnz .LBB0_512
	s_cmp_eq_u32 s99, 0
	s_cbranch_scc1 .Lakv1_plain
	s_waitcnt vmcnt(3)
	ds_write_b128 v178, v[116:119] offset:17408
	s_waitcnt vmcnt(2)
	ds_write_b128 v178, v[112:115] offset:26112
	s_branch .LBB0_512
.Lakv1_plain:
	s_waitcnt vmcnt(1)
	ds_write_b128 v178, v[116:119] offset:17408
	s_waitcnt vmcnt(0)
	ds_write_b128 v178, v[112:115] offset:26112
.LBB0_512:
	s_mov_b32 s99, 0
	s_cmp_gt_u32 s75, 32
	s_cbranch_scc1 .LBB0_515
	s_add_i32 s2, s46, 3
	s_cmp_lt_u32 s2, 4
	s_cbranch_scc1 .LBB0_515
	v_subrev_u32_e32 v1, 32, v173
	v_lshlrev_b32_e32 v1, s43, v1
	v_add_u32_e32 v1, s97, v1
	v_lshl_add_u32 v1, v1, 11, v183
	global_load_dwordx4 v[116:119], v1, s[80:81]
	global_load_dwordx4 v[112:115], v1, s[82:83]
	s_mov_b32 s99, 1

; #define LAS __attribute__((address_space(3)))
; #define MFMA32(a, b, c) __builtin_amdgcn_mfma_f32_32x32x16_bf16((a), (b), (c), 0, 0, 0)
; __device__ __forceinline__ void attn_tile(const LAS bf16_t* kl, unsigned vaddr, int kt, const bf16x8 (&qf)[8], f32x16 (&o)[4], float& mrun, float& lrun, int r, int h, int rr, int p, int hd, size_t qtok,
;                                           bf16_t* __restrict__ OP, float* __restrict__ LSE) {
;     const float scl = 0.08838834764831845f * 1.4426950408889634f;
;     f32x16 s, sb;
; #pragma unroll
;     for (int i = 0; i < 16; ++i) { s[i] = 0.f; sb[i] = 0.f; }
;     {
;         bf16x8 kf[8];
; #pragma unroll
;         for (int j = 0; j < 8; ++j) kf[j] = *(const LAS bf16x8*)(kl + r * 136 + 16 * j + 8 * h);
;         __builtin_amdgcn_sched_barrier(0);
; #pragma unroll
;         for (int j = 0; j < 8; j += 2) { s = MFMA32(kf[j], qf[j], s); sb = MFMA32(kf[j + 1], qf[j + 1], sb); }
;     }
; #pragma unroll
;     for (int i = 0; i < 16; ++i) s[i] += sb[i];
;     s16x4 tq0[8];
;     tr_issue8<0>(vaddr, tq0);
;     if (kt == 0) {
; #pragma unroll
;         for (int i = 0; i < 16; ++i) s[i] = (((i & 3) + 8 * (i >> 2)) >= rr) ? s[i] : -INFINITY;
;     } else if (kt == 4) {
; #pragma unroll
;         for (int i = 0; i < 16; ++i) s[i] = (((i & 3) + 8 * (i >> 2)) <= rr) ? s[i] : -INFINITY;
;     }
.LBB0_517:
	s_lshr_b32 s2, s48, 3
	s_min_u32 s2, s2, 3
	s_lshl_b32 s2, s2, 3
	s_sub_i32 s2, 0, s2
	s_cmp_ge_u32 s75, s78
	s_cselect_b32 s2, s2, 0
	s_add_i32 s2, s3, s2
	s_add_i32 s2, s2, s75
	v_cndmask_b32_e64 v1, 0, 1, s[38:39]
	s_cmp_gt_u32 s2, 4
	v_cmp_ne_u32_e64 s[70:71], 1, v1
	s_cbranch_scc1 .LBB0_533
	s_and_b64 vcc, exec, s[70:71]
	s_cbranch_vccnz .LBB0_524
	v_add_u32_e32 v1, v165, v164
	ds_read_b128 v[2:5], v1
	ds_read_b128 v[6:9], v1 offset:32
	ds_read_b128 v[10:13], v1 offset:64
	ds_read_b128 v[160:163], v1 offset:96
	ds_read_b128 v[188:191], v1 offset:128
	ds_read_b128 v[192:195], v1 offset:160
	ds_read_b128 v[196:199], v1 offset:192
	ds_read_b128 v[200:203], v1 offset:224
	s_waitcnt vmcnt(2) lgkmcnt(7)
	v_mfma_f32_32x32x16_bf16 v[80:95], v[2:5], v[120:123], 0
	s_cmp_gt_i32 s2, 3
	s_mov_b64 s[38:39], -1
	s_waitcnt lgkmcnt(6)
	v_mfma_f32_32x32x16_bf16 v[96:111], v[6:9], v[124:127], 0
	s_waitcnt lgkmcnt(5)
	v_mfma_f32_32x32x16_bf16 v[80:95], v[10:13], v[128:131], v[80:95]
	s_waitcnt lgkmcnt(4)
	v_mfma_f32_32x32x16_bf16 v[96:111], v[160:163], v[132:135], v[96:111]
	ds_read_b64_tr_b16 v[160:161], v176 offset:0
	ds_read_b64_tr_b16 v[162:163], v176 offset:0x880
	ds_read_b64_tr_b16 v[10:11], v176 offset:64
	ds_read_b64_tr_b16 v[12:13], v176 offset:0x8c0
	ds_read_b64_tr_b16 v[6:7], v176 offset:0x80
	ds_read_b64_tr_b16 v[8:9], v176 offset:0x900
	ds_read_b64_tr_b16 v[2:3], v176 offset:0xc0
	ds_read_b64_tr_b16 v[4:5], v176 offset:0x940
	s_waitcnt lgkmcnt(3)
	v_mfma_f32_32x32x16_bf16 v[80:95], v[188:191], v[140:143], v[80:95]
	s_waitcnt lgkmcnt(2)
	v_mfma_f32_32x32x16_bf16 v[96:111], v[192:195], v[144:147], v[96:111]
	s_waitcnt lgkmcnt(1)
	v_mfma_f32_32x32x16_bf16 v[80:95], v[196:199], v[148:151], v[80:95]
	s_waitcnt lgkmcnt(0)
	v_mfma_f32_32x32x16_bf16 v[96:111], v[200:203], v[136:139], v[96:111]
	s_nop 11
	v_pk_add_f32 v[14:15], v[94:95], v[110:111]
	v_pk_add_f32 v[92:93], v[92:93], v[108:109]
	v_pk_add_f32 v[90:91], v[90:91], v[106:107]
	v_pk_add_f32 v[88:89], v[88:89], v[104:105]
	v_pk_add_f32 v[86:87], v[86:87], v[102:103]
	v_pk_add_f32 v[84:85], v[84:85], v[100:101]
	v_pk_add_f32 v[82:83], v[82:83], v[98:99]
	v_pk_add_f32 v[80:81], v[80:81], v[96:97]
	s_cbranch_scc0 .LBB0_521
	v_cndmask_b32_e64 v109, v80, v185, s[0:1]
	v_cndmask_b32_e64 v108, v81, v185, s[4:5]
	v_cndmask_b32_e64 v107, v82, v185, s[6:7]
	v_cndmask_b32_e64 v106, v83, v185, s[8:9]
	v_cndmask_b32_e64 v105, v84, v185, s[10:11]
	v_cndmask_b32_e64 v99, v85, v185, s[12:13]
	v_cndmask_b32_e64 v101, v86, v185, s[14:15]
	v_cndmask_b32_e64 v103, v87, v185, s[16:17]
	v_cndmask_b32_e64 v104, v88, v185, s[18:19]
	v_cndmask_b32_e64 v102, v89, v185, s[20:21]
	v_cndmask_b32_e64 v100, v90, v185, s[22:23]
	v_cndmask_b32_e64 v98, v91, v185, s[24:25]
	v_cndmask_b32_e64 v97, v92, v185, s[26:27]
	v_cndmask_b32_e64 v96, v93, v185, s[28:29]
	v_cndmask_b32_e64 v95, v14, v185, s[30:31]
	v_cndmask_b32_e64 v94, v15, v185, s[34:35]
	s_mov_b64 s[38:39], 0

.LBB0_533:
	s_cmp_lt_u32 s75, 34
	s_waitcnt lgkmcnt(0)
	s_barrier
	s_cselect_b64 s[40:41], -1, 0
	s_cmp_gt_u32 s75, 33
	s_cselect_b64 s[38:39], -1, 0
	s_and_b64 vcc, exec, s[38:39]
	s_cbranch_vccnz .LBB0_536
	s_add_i32 s2, s46, 2
	s_and_b32 s2, s2, 0x7fffffc
	s_cmp_eq_u32 s2, 0
	s_cbranch_scc1 .LBB0_536
	s_cmp_eq_u32 s99, 0
	s_cbranch_scc1 .Lakv2_plain
	s_waitcnt vmcnt(3)
	ds_write_b128 v178, v[152:155]
	s_waitcnt vmcnt(2)
	ds_write_b128 v178, v[156:159] offset:8704
	s_branch .LBB0_536
.Lakv2_plain:
	s_waitcnt vmcnt(1)
	ds_write_b128 v178, v[152:155]
	s_waitcnt vmcnt(0)
	ds_write_b128 v178, v[156:159] offset:8704
.LBB0_536:
	s_mov_b32 s99, 0
	s_cmp_gt_u32 s75, 31
	s_cbranch_scc1 .LBB0_538
	v_lshlrev_b32_e32 v1, s43, v173
	v_add_u32_e32 v1, s97, v1
	v_lshl_add_u32 v1, v1, 11, v183
	global_load_dwordx4 v[152:155], v1, s[80:81]
	global_load_dwordx4 v[156:159], v1, s[82:83]
	s_mov_b32 s99, 1

; #define LAS __attribute__((address_space(3)))
; #define MFMA32(a, b, c) __builtin_amdgcn_mfma_f32_32x32x16_bf16((a), (b), (c), 0, 0, 0)
; __device__ __forceinline__ void attn_tile(const LAS bf16_t* kl, unsigned vaddr, int kt, const bf16x8 (&qf)[8], f32x16 (&o)[4], float& mrun, float& lrun, int r, int h, int rr, int p, int hd, size_t qtok,
;                                           bf16_t* __restrict__ OP, float* __restrict__ LSE) {
;     const float scl = 0.08838834764831845f * 1.4426950408889634f;
;     f32x16 s, sb;
; #pragma unroll
;     for (int i = 0; i < 16; ++i) { s[i] = 0.f; sb[i] = 0.f; }
;     {
;         bf16x8 kf[8];
; #pragma unroll
;         for (int j = 0; j < 8; ++j) kf[j] = *(const LAS bf16x8*)(kl + r * 136 + 16 * j + 8 * h);
;         __builtin_amdgcn_sched_barrier(0);
; #pragma unroll
;         for (int j = 0; j < 8; j += 2) { s = MFMA32(kf[j], qf[j], s); sb = MFMA32(kf[j + 1], qf[j + 1], sb); }
;     }
; #pragma unroll
;     for (int i = 0; i < 16; ++i) s[i] += sb[i];
;     s16x4 tq0[8];
;     tr_issue8<0>(vaddr, tq0);
;     if (kt == 0) {
; #pragma unroll
;         for (int i = 0; i < 16; ++i) s[i] = (((i & 3) + 8 * (i >> 2)) >= rr) ? s[i] : -INFINITY;
;     } else if (kt == 4) {
; #pragma unroll
;         for (int i = 0; i < 16; ++i) s[i] = (((i & 3) + 8 * (i >> 2)) <= rr) ? s[i] : -INFINITY;
;     }
.LBB0_541:
	s_sub_i32 s2, 0, s45
	s_and_b64 s[36:37], s[84:85], exec
	s_cselect_b32 s2, 0, s2
	s_add_i32 s2, s3, s2
	s_add_i32 s2, s2, s75
	s_add_i32 s33, s2, 1
	s_cmp_gt_u32 s33, 4
	s_cbranch_scc1 .LBB0_509
	s_and_b64 vcc, exec, s[70:71]
	s_cbranch_vccnz .LBB0_507
	v_add_u32_e32 v1, v165, v164
	ds_read_b128 v[2:5], v1 offset:17408
	ds_read_b128 v[6:9], v1 offset:17440
	ds_read_b128 v[10:13], v1 offset:17472
	ds_read_b128 v[160:163], v1 offset:17504
	ds_read_b128 v[188:191], v1 offset:17536
	ds_read_b128 v[192:195], v1 offset:17568
	ds_read_b128 v[196:199], v1 offset:17600
	ds_read_b128 v[200:203], v1 offset:17632
	s_waitcnt vmcnt(2) lgkmcnt(7)
	v_mfma_f32_32x32x16_bf16 v[80:95], v[2:5], v[120:123], 0
	s_cmp_gt_i32 s33, 3
	s_mov_b64 s[36:37], -1
	s_waitcnt lgkmcnt(6)
	v_mfma_f32_32x32x16_bf16 v[96:111], v[6:9], v[124:127], 0
	s_waitcnt lgkmcnt(5)
	v_mfma_f32_32x32x16_bf16 v[80:95], v[10:13], v[128:131], v[80:95]
	s_waitcnt lgkmcnt(4)
	v_mfma_f32_32x32x16_bf16 v[96:111], v[160:163], v[132:135], v[96:111]
	ds_read_b64_tr_b16 v[160:161], v177 offset:0
	ds_read_b64_tr_b16 v[162:163], v177 offset:0x880
	ds_read_b64_tr_b16 v[10:11], v177 offset:64
	ds_read_b64_tr_b16 v[12:13], v177 offset:0x8c0
	ds_read_b64_tr_b16 v[6:7], v177 offset:0x80
	ds_read_b64_tr_b16 v[8:9], v177 offset:0x900
	ds_read_b64_tr_b16 v[2:3], v177 offset:0xc0
	ds_read_b64_tr_b16 v[4:5], v177 offset:0x940
	s_waitcnt lgkmcnt(3)
	v_mfma_f32_32x32x16_bf16 v[80:95], v[188:191], v[140:143], v[80:95]
	s_waitcnt lgkmcnt(2)
	v_mfma_f32_32x32x16_bf16 v[96:111], v[192:195], v[144:147], v[96:111]
	s_waitcnt lgkmcnt(1)
	v_mfma_f32_32x32x16_bf16 v[80:95], v[196:199], v[148:151], v[80:95]
	s_waitcnt lgkmcnt(0)
	v_mfma_f32_32x32x16_bf16 v[96:111], v[200:203], v[136:139], v[96:111]
	s_nop 11
	v_pk_add_f32 v[14:15], v[94:95], v[110:111]
	v_pk_add_f32 v[92:93], v[92:93], v[108:109]
	v_pk_add_f32 v[90:91], v[90:91], v[106:107]
	v_pk_add_f32 v[88:89], v[88:89], v[104:105]
	v_pk_add_f32 v[86:87], v[86:87], v[102:103]
	v_pk_add_f32 v[84:85], v[84:85], v[100:101]
	v_pk_add_f32 v[82:83], v[82:83], v[98:99]
	v_pk_add_f32 v[80:81], v[80:81], v[96:97]
	s_cbranch_scc0 .LBB0_545
	v_cndmask_b32_e64 v109, v80, v185, s[0:1]
	v_cndmask_b32_e64 v108, v81, v185, s[4:5]
	v_cndmask_b32_e64 v107, v82, v185, s[6:7]
	v_cndmask_b32_e64 v106, v83, v185, s[8:9]
	v_cndmask_b32_e64 v105, v84, v185, s[10:11]
	v_cndmask_b32_e64 v99, v85, v185, s[12:13]
	v_cndmask_b32_e64 v101, v86, v185, s[14:15]
	v_cndmask_b32_e64 v103, v87, v185, s[16:17]
	v_cndmask_b32_e64 v104, v88, v185, s[18:19]
	v_cndmask_b32_e64 v102, v89, v185, s[20:21]
	v_cndmask_b32_e64 v100, v90, v185, s[22:23]
	v_cndmask_b32_e64 v98, v91, v185, s[24:25]
	v_cndmask_b32_e64 v97, v92, v185, s[26:27]
	v_cndmask_b32_e64 v96, v93, v185, s[28:29]
	v_cndmask_b32_e64 v95, v14, v185, s[30:31]
	v_cndmask_b32_e64 v94, v15, v185, s[34:35]
	s_mov_b64 s[36:37], 0

; #define LAS __attribute__((address_space(3)))
; __device__ __forceinline__ void attn_run_coop(int nq, int p, int hd, int res, int x0, const bf16_t* __restrict__ AQ, const bf16_t* __restrict__ AK, const bf16_t* __restrict__ AV, bf16_t* __restrict__ OP, float* __restrict__ LSE, ...
;     const int lg = (p == 0) ? 0 : (p == 1) ? 2 : 4, dl = 1 << lg;
;     const int r = lane & 31, h = lane >> 5, lkey = lane >> 4, lch = lane & 15, rr = r - 4 * h, myrow = 4 * w + lkey;
;     LAS bf16_t* const K0 = lbase; LAS bf16_t* const V0 = lbase + 4352; LAS bf16_t* const K1 = lbase + 8704; LAS bf16_t* const V1 = lbase + 8704 + 4352;
;     const unsigned lanepart = (unsigned)(((4 * (lane >> 5) + ((lane & 15) >> 2)) * 136 + 16 * ((lane >> 4) & 1) + 4 * (lane & 3)) * 2);
;     const unsigned vaddr0 = (unsigned)(size_t)V0 + lanepart, vaddr1 = (unsigned)(size_t)V1 + lanepart;
;     u32x4 kA = (u32x4){0u, 0u, 0u, 0u}, vA = kA, kB = kA, vB = kA;
;     bf16x8 qf[8]; f32x16 o[4]; float mrun = -INFINITY, lrun = 0.f; size_t qtok = 0;
; #pragma unroll
;     for (int j = 0; j < 8; ++j) qf[j] = (bf16x8){0, 0, 0, 0, 0, 0, 0, 0};
; #pragma unroll
;     for (int dt = 0; dt < 4; ++dt)
; #pragma unroll
;         for (int i = 0; i < 16; ++i) o[dt][i] = 0.f;
;     if (ATT_TILE_VALID(0)) { const unsigned vo = ATT_VOFF(0); kA = *(const u32x4*)((const char*)AK + vo); vA = *(const u32x4*)((const char*)AV + vo); }
;     if (ATT_TILE_VALID(1)) { const unsigned vo = ATT_VOFF(1); kB = *(const u32x4*)((const char*)AK + vo); vB = *(const u32x4*)((const char*)AV + vo); }
;     ATT_BOOK(-1);
;     if (ATT_TILE_VALID(0)) { *(LAS u32x4*)(K0 + myrow * 136 + 8 * lch) = kA; *(LAS u32x4*)(V0 + myrow * 136 + 8 * lch) = vA; }
;     if (ATT_TILE_VALID(2)) { const unsigned vo = ATT_VOFF(2); kA = *(const u32x4*)((const char*)AK + vo); vA = *(const u32x4*)((const char*)AV + vo); }
;     asm volatile("s_waitcnt lgkmcnt(0)" ::: "memory"); __builtin_amdgcn_s_barrier(); asm volatile("" ::: "memory");
.LBB0_567:
	s_lshl_b32 s36, s79, 1
	s_add_u32 s36, s90, s36
	s_waitcnt vmcnt(10)
	v_mov_b32_e32 v0, 0
	s_addc_u32 s37, s91, 0
	v_lshlrev_b32_e32 v2, 1, v168
	v_mov_b32_e32 v3, v0
	v_lshl_add_u64 v[2:3], s[36:37], 0, v[2:3]
	s_mov_b64 s[36:37], 0x1d700000
	v_lshl_add_u64 v[168:169], v[2:3], 0, s[36:37]
	v_readlane_b32 s36, v244, 3
	s_lshl_b32 s36, s36, 2
	s_add_u32 s36, s90, s36
	s_addc_u32 s37, s91, 0
	s_add_u32 s76, s36, 0x4600000
	s_addc_u32 s77, s37, 0
	v_readlane_b32 s36, v245, 0
	v_readlane_b32 s37, v245, 1
	s_bfe_u32 s36, s36, 0x10003
	s_lshl_b32 s37, s36, 24
	s_lshl_b32 s39, s78, 17
	s_add_i32 s37, s37, s39
	s_add_i32 s33, s38, s33
	v_lshlrev_b32_e32 v2, 15, v179
	s_add_i32 s33, s33, s37
	v_lshlrev_b32_e32 v1, 4, v180
	v_add3_u32 v179, s33, v2, v8
	s_lshl_b32 s33, s36, 13
	v_add_u32_e32 v180, s2, v1
	s_add_i32 s2, s2, s33
	v_add_u32_e32 v1, s2, v1
	v_add_u32_e32 v172, 0x200, v1
	v_mov_b32_e32 v173, v0
	v_and_b32_e32 v1, 32, v209
	v_lshlrev_b64 v[2:3], 11, v[172:173]
	v_lshrrev_b32_e32 v1, 1, v1
	v_or3_b32 v2, v2, s44, v1
	s_waitcnt lgkmcnt(0)
	s_barrier
	v_lshl_add_u64 v[2:3], s[90:91], 0, v[2:3]
	s_mov_b64 s[36:37], 0xb700080
	v_mov_b32_e32 v14, v0
	v_mov_b32_e32 v15, v0
	v_lshl_add_u64 v[174:175], v[2:3], 0, s[36:37]
	v_mov_b32_e32 v1, v0
	v_mov_b32_e32 v2, v0
	v_mov_b32_e32 v3, v0
	v_mov_b32_e32 v4, v0
	v_mov_b32_e32 v5, v0
	v_mov_b32_e32 v6, v0
	v_mov_b32_e32 v7, v0
	v_mov_b32_e32 v8, v0
	v_mov_b32_e32 v9, v0
	v_mov_b32_e32 v10, v0
	v_mov_b32_e32 v11, v0
	v_mov_b32_e32 v12, v0
	v_mov_b32_e32 v13, v0
	v_mov_b64_e32 v[30:31], v[14:15]
	v_mov_b64_e32 v[46:47], v[14:15]
	v_mov_b64_e32 v[62:63], v[14:15]
	v_mov_b64_e32 v[78:79], v[14:15]
	s_mov_b32 s44, 0
	v_mov_b32_e32 v181, 0xff800000
	s_mov_b32 s43, 0x3e0293ee
	v_mov_b64_e32 v[28:29], v[12:13]
	v_mov_b64_e32 v[26:27], v[10:11]
	v_mov_b64_e32 v[24:25], v[8:9]
	v_mov_b64_e32 v[22:23], v[6:7]
	v_mov_b64_e32 v[20:21], v[4:5]
	v_mov_b64_e32 v[18:19], v[2:3]
	v_mov_b64_e32 v[16:17], v[0:1]
	v_mov_b64_e32 v[44:45], v[12:13]
	v_mov_b64_e32 v[42:43], v[10:11]
	v_mov_b64_e32 v[40:41], v[8:9]
	v_mov_b64_e32 v[38:39], v[6:7]
	v_mov_b64_e32 v[36:37], v[4:5]
	v_mov_b64_e32 v[34:35], v[2:3]
	v_mov_b64_e32 v[32:33], v[0:1]
	v_mov_b64_e32 v[60:61], v[12:13]
	v_mov_b64_e32 v[58:59], v[10:11]
	v_mov_b64_e32 v[56:57], v[8:9]
	v_mov_b64_e32 v[54:55], v[6:7]
	v_mov_b64_e32 v[52:53], v[4:5]
	v_mov_b64_e32 v[50:51], v[2:3]
	v_mov_b64_e32 v[48:49], v[0:1]
	v_mov_b64_e32 v[76:77], v[12:13]
	v_mov_b64_e32 v[74:75], v[10:11]
	v_mov_b64_e32 v[72:73], v[8:9]
	v_mov_b64_e32 v[70:71], v[6:7]
	v_mov_b64_e32 v[68:69], v[4:5]
	v_mov_b64_e32 v[66:67], v[2:3]
	v_mov_b64_e32 v[64:65], v[0:1]
	v_mov_b32_e32 v182, 0
	v_mov_b32_e32 v183, 0xff800000
	s_mov_b32 s99, 0
	s_branch .LBB0_571

.LBB0_571:
	s_add_i32 s45, s42, s44
	s_and_b32 s2, s45, 0x7fffffc
	s_cmp_lg_u32 s2, 0
	s_cselect_b64 s[36:37], -1, 0
	s_cmp_eq_u32 s2, 0
	s_cbranch_scc1 .LBB0_573
	s_cmp_eq_u32 s99, 0
	s_cbranch_scc1 .Lakv3_plain
	s_waitcnt vmcnt(3)
	ds_write_b128 v178, v[116:119] offset:17408
	s_waitcnt vmcnt(2)
	ds_write_b128 v178, v[112:115] offset:26112
	s_branch .LBB0_573

.LBB0_573:
	s_mov_b32 s99, 0
	s_cmp_gt_u32 s44, 16
	s_cbranch_scc1 .LBB0_576
	s_add_i32 s2, s45, 3
	s_cmp_lt_u32 s2, 4
	s_cbranch_scc1 .LBB0_576
	v_add_u32_e32 v1, 0xfff00000, v179
	global_load_dwordx4 v[116:119], v1, s[80:81]
	global_load_dwordx4 v[112:115], v1, s[82:83]
	s_mov_b32 s99, 1

; #define LAS __attribute__((address_space(3)))
; #define MFMA32(a, b, c) __builtin_amdgcn_mfma_f32_32x32x16_bf16((a), (b), (c), 0, 0, 0)
; __device__ __forceinline__ void attn_tile(const LAS bf16_t* kl, unsigned vaddr, int kt, const bf16x8 (&qf)[8], f32x16 (&o)[4], float& mrun, float& lrun, int r, int h, int rr, int p, int hd, size_t qtok,
;                                           bf16_t* __restrict__ OP, float* __restrict__ LSE) {
;     const float scl = 0.08838834764831845f * 1.4426950408889634f;
;     f32x16 s, sb;
; #pragma unroll
;     for (int i = 0; i < 16; ++i) { s[i] = 0.f; sb[i] = 0.f; }
;     {
;         bf16x8 kf[8];
; #pragma unroll
;         for (int j = 0; j < 8; ++j) kf[j] = *(const LAS bf16x8*)(kl + r * 136 + 16 * j + 8 * h);
;         __builtin_amdgcn_sched_barrier(0);
; #pragma unroll
;         for (int j = 0; j < 8; j += 2) { s = MFMA32(kf[j], qf[j], s); sb = MFMA32(kf[j + 1], qf[j + 1], sb); }
;     }
; #pragma unroll
;     for (int i = 0; i < 16; ++i) s[i] += sb[i];
;     s16x4 tq0[8];
;     tr_issue8<0>(vaddr, tq0);
;     if (kt == 0) {
; #pragma unroll
;         for (int i = 0; i < 16; ++i) s[i] = (((i & 3) + 8 * (i >> 2)) >= rr) ? s[i] : -INFINITY;
;     } else if (kt == 4) {
; #pragma unroll
;         for (int i = 0; i < 16; ++i) s[i] = (((i & 3) + 8 * (i >> 2)) <= rr) ? s[i] : -INFINITY;
;     }
.LBB0_578:
	s_cmp_lt_u32 s44, s78
	s_cselect_b64 s[38:39], -1, 0
	s_cmp_lt_u32 s47, 8
	s_cselect_b64 s[40:41], -1, 0
	s_or_b64 s[38:39], s[38:39], s[40:41]
	s_and_b64 s[38:39], s[38:39], exec
	s_cselect_b32 s2, 0, -8
	s_add_i32 s2, s3, s2
	s_add_i32 s2, s2, s44
	v_cndmask_b32_e64 v1, 0, 1, s[36:37]
	s_cmp_gt_u32 s2, 4
	v_cmp_ne_u32_e64 s[70:71], 1, v1
	s_cbranch_scc1 .LBB0_594
	s_and_b64 vcc, exec, s[70:71]
	s_cbranch_vccnz .LBB0_585
	v_add_u32_e32 v1, v165, v164
	ds_read_b128 v[2:5], v1
	ds_read_b128 v[6:9], v1 offset:32
	ds_read_b128 v[10:13], v1 offset:64
	ds_read_b128 v[160:163], v1 offset:96
	ds_read_b128 v[184:187], v1 offset:128
	ds_read_b128 v[188:191], v1 offset:160
	ds_read_b128 v[192:195], v1 offset:192
	ds_read_b128 v[196:199], v1 offset:224
	s_waitcnt vmcnt(2) lgkmcnt(7)
	v_mfma_f32_32x32x16_bf16 v[80:95], v[2:5], v[120:123], 0
	s_cmp_gt_i32 s2, 3
	s_mov_b64 s[36:37], -1
	s_waitcnt lgkmcnt(6)
	v_mfma_f32_32x32x16_bf16 v[96:111], v[6:9], v[124:127], 0
	s_waitcnt lgkmcnt(5)
	v_mfma_f32_32x32x16_bf16 v[80:95], v[10:13], v[128:131], v[80:95]
	s_waitcnt lgkmcnt(4)
	v_mfma_f32_32x32x16_bf16 v[96:111], v[160:163], v[132:135], v[96:111]
	ds_read_b64_tr_b16 v[160:161], v176 offset:0
	ds_read_b64_tr_b16 v[162:163], v176 offset:0x880
	ds_read_b64_tr_b16 v[10:11], v176 offset:64
	ds_read_b64_tr_b16 v[12:13], v176 offset:0x8c0
	ds_read_b64_tr_b16 v[6:7], v176 offset:0x80
	ds_read_b64_tr_b16 v[8:9], v176 offset:0x900
	ds_read_b64_tr_b16 v[2:3], v176 offset:0xc0
	ds_read_b64_tr_b16 v[4:5], v176 offset:0x940
	s_waitcnt lgkmcnt(3)
	v_mfma_f32_32x32x16_bf16 v[80:95], v[184:187], v[136:139], v[80:95]
	s_waitcnt lgkmcnt(2)
	v_mfma_f32_32x32x16_bf16 v[96:111], v[188:191], v[140:143], v[96:111]
	s_waitcnt lgkmcnt(1)
	v_mfma_f32_32x32x16_bf16 v[80:95], v[192:195], v[144:147], v[80:95]
	s_waitcnt lgkmcnt(0)
	v_mfma_f32_32x32x16_bf16 v[96:111], v[196:199], v[148:151], v[96:111]
	s_nop 11
	v_pk_add_f32 v[14:15], v[94:95], v[110:111]
	v_pk_add_f32 v[92:93], v[92:93], v[108:109]
	v_pk_add_f32 v[90:91], v[90:91], v[106:107]
	v_pk_add_f32 v[88:89], v[88:89], v[104:105]
	v_pk_add_f32 v[86:87], v[86:87], v[102:103]
	v_pk_add_f32 v[84:85], v[84:85], v[100:101]
	v_pk_add_f32 v[82:83], v[82:83], v[98:99]
	v_pk_add_f32 v[80:81], v[80:81], v[96:97]
	s_cbranch_scc0 .LBB0_582
	v_cndmask_b32_e64 v109, v80, v181, s[0:1]
	v_cndmask_b32_e64 v108, v81, v181, s[4:5]
	v_cndmask_b32_e64 v107, v82, v181, s[6:7]
	v_cndmask_b32_e64 v106, v83, v181, s[8:9]
	v_cndmask_b32_e64 v105, v84, v181, s[10:11]
	v_cndmask_b32_e64 v99, v85, v181, s[12:13]
	v_cndmask_b32_e64 v101, v86, v181, s[14:15]
	v_cndmask_b32_e64 v103, v87, v181, s[16:17]
	v_cndmask_b32_e64 v104, v88, v181, s[18:19]
	v_cndmask_b32_e64 v102, v89, v181, s[20:21]
	v_cndmask_b32_e64 v100, v90, v181, s[22:23]
	v_cndmask_b32_e64 v98, v91, v181, s[24:25]
	v_cndmask_b32_e64 v97, v92, v181, s[26:27]
	v_cndmask_b32_e64 v96, v93, v181, s[28:29]
	v_cndmask_b32_e64 v95, v14, v181, s[30:31]
	v_cndmask_b32_e64 v94, v15, v181, s[34:35]
	s_mov_b64 s[36:37], 0

.LBB0_594:
	s_cmp_lt_u32 s44, 18
	s_cselect_b64 s[38:39], -1, 0
	s_cmp_gt_u32 s44, 17
	s_cselect_b64 s[36:37], -1, 0
	s_add_i32 s2, s45, 2
	s_cmp_gt_u32 s2, 3
	s_waitcnt lgkmcnt(0)
	s_barrier
	s_cselect_b64 s[40:41], -1, 0
	s_and_b64 s[48:49], s[38:39], s[40:41]
	s_andn2_b64 vcc, exec, s[48:49]
	s_cbranch_vccnz .LBB0_596
	s_cmp_eq_u32 s99, 0
	s_cbranch_scc1 .Lakv4_plain
	s_waitcnt vmcnt(3)
	ds_write_b128 v178, v[152:155]
	s_waitcnt vmcnt(2)
	ds_write_b128 v178, v[156:159] offset:8704
	s_branch .LBB0_596

.LBB0_596:
	s_mov_b32 s99, 0
	s_cmp_gt_u32 s44, 15
	s_cbranch_scc1 .LBB0_598
	global_load_dwordx4 v[152:155], v179, s[80:81]
	global_load_dwordx4 v[156:159], v179, s[82:83]
	s_mov_b32 s99, 1

; #define LAS __attribute__((address_space(3)))
; #define MFMA32(a, b, c) __builtin_amdgcn_mfma_f32_32x32x16_bf16((a), (b), (c), 0, 0, 0)
; __device__ __forceinline__ void attn_tile(const LAS bf16_t* kl, unsigned vaddr, int kt, const bf16x8 (&qf)[8], f32x16 (&o)[4], float& mrun, float& lrun, int r, int h, int rr, int p, int hd, size_t qtok,
;                                           bf16_t* __restrict__ OP, float* __restrict__ LSE) {
;     const float scl = 0.08838834764831845f * 1.4426950408889634f;
;     f32x16 s, sb;
; #pragma unroll
;     for (int i = 0; i < 16; ++i) { s[i] = 0.f; sb[i] = 0.f; }
;     {
;         bf16x8 kf[8];
; #pragma unroll
;         for (int j = 0; j < 8; ++j) kf[j] = *(const LAS bf16x8*)(kl + r * 136 + 16 * j + 8 * h);
;         __builtin_amdgcn_sched_barrier(0);
; #pragma unroll
;         for (int j = 0; j < 8; j += 2) { s = MFMA32(kf[j], qf[j], s); sb = MFMA32(kf[j + 1], qf[j + 1], sb); }
;     }
; #pragma unroll
;     for (int i = 0; i < 16; ++i) s[i] += sb[i];
;     s16x4 tq0[8];
;     tr_issue8<0>(vaddr, tq0);
;     if (kt == 0) {
; #pragma unroll
;         for (int i = 0; i < 16; ++i) s[i] = (((i & 3) + 8 * (i >> 2)) >= rr) ? s[i] : -INFINITY;
;     } else if (kt == 4) {
; #pragma unroll
;         for (int i = 0; i < 16; ++i) s[i] = (((i & 3) + 8 * (i >> 2)) <= rr) ? s[i] : -INFINITY;
;     }
.LBB0_601:
	s_and_b64 s[38:39], s[74:75], exec
	s_cselect_b32 s2, 0, -8
	s_add_i32 s2, s3, s2
	s_add_i32 s2, s2, s44
	s_add_i32 s33, s2, 1
	s_cmp_gt_u32 s33, 4
	s_cbranch_scc1 .LBB0_570
	s_and_b64 vcc, exec, s[70:71]
	s_cbranch_vccnz .LBB0_568
	v_add_u32_e32 v1, v165, v164
	ds_read_b128 v[2:5], v1 offset:17408
	ds_read_b128 v[6:9], v1 offset:17440
	ds_read_b128 v[10:13], v1 offset:17472
	ds_read_b128 v[160:163], v1 offset:17504
	ds_read_b128 v[184:187], v1 offset:17536
	ds_read_b128 v[188:191], v1 offset:17568
	ds_read_b128 v[192:195], v1 offset:17600
	ds_read_b128 v[196:199], v1 offset:17632
	s_waitcnt vmcnt(2) lgkmcnt(7)
	v_mfma_f32_32x32x16_bf16 v[80:95], v[2:5], v[120:123], 0
	s_cmp_gt_i32 s33, 3
	s_mov_b64 s[38:39], -1
	s_waitcnt lgkmcnt(6)
	v_mfma_f32_32x32x16_bf16 v[96:111], v[6:9], v[124:127], 0
	s_waitcnt lgkmcnt(5)
	v_mfma_f32_32x32x16_bf16 v[80:95], v[10:13], v[128:131], v[80:95]
	s_waitcnt lgkmcnt(4)
	v_mfma_f32_32x32x16_bf16 v[96:111], v[160:163], v[132:135], v[96:111]
	ds_read_b64_tr_b16 v[160:161], v177 offset:0
	ds_read_b64_tr_b16 v[162:163], v177 offset:0x880
	ds_read_b64_tr_b16 v[10:11], v177 offset:64
	ds_read_b64_tr_b16 v[12:13], v177 offset:0x8c0
	ds_read_b64_tr_b16 v[6:7], v177 offset:0x80
	ds_read_b64_tr_b16 v[8:9], v177 offset:0x900
	ds_read_b64_tr_b16 v[2:3], v177 offset:0xc0
	ds_read_b64_tr_b16 v[4:5], v177 offset:0x940
	s_waitcnt lgkmcnt(3)
	v_mfma_f32_32x32x16_bf16 v[80:95], v[184:187], v[136:139], v[80:95]
	s_waitcnt lgkmcnt(2)
	v_mfma_f32_32x32x16_bf16 v[96:111], v[188:191], v[140:143], v[96:111]
	s_waitcnt lgkmcnt(1)
	v_mfma_f32_32x32x16_bf16 v[80:95], v[192:195], v[144:147], v[80:95]
	s_waitcnt lgkmcnt(0)
	v_mfma_f32_32x32x16_bf16 v[96:111], v[196:199], v[148:151], v[96:111]
	s_nop 11
	v_pk_add_f32 v[14:15], v[94:95], v[110:111]
	v_pk_add_f32 v[92:93], v[92:93], v[108:109]
	v_pk_add_f32 v[90:91], v[90:91], v[106:107]
	v_pk_add_f32 v[88:89], v[88:89], v[104:105]
	v_pk_add_f32 v[86:87], v[86:87], v[102:103]
	v_pk_add_f32 v[84:85], v[84:85], v[100:101]
	v_pk_add_f32 v[82:83], v[82:83], v[98:99]
	v_pk_add_f32 v[80:81], v[80:81], v[96:97]
	s_cbranch_scc0 .LBB0_605
	v_cndmask_b32_e64 v109, v80, v181, s[0:1]
	v_cndmask_b32_e64 v108, v81, v181, s[4:5]
	v_cndmask_b32_e64 v107, v82, v181, s[6:7]
	v_cndmask_b32_e64 v106, v83, v181, s[8:9]
	v_cndmask_b32_e64 v105, v84, v181, s[10:11]
	v_cndmask_b32_e64 v99, v85, v181, s[12:13]
	v_cndmask_b32_e64 v101, v86, v181, s[14:15]
	v_cndmask_b32_e64 v103, v87, v181, s[16:17]
	v_cndmask_b32_e64 v104, v88, v181, s[18:19]
	v_cndmask_b32_e64 v102, v89, v181, s[20:21]
	v_cndmask_b32_e64 v100, v90, v181, s[22:23]
	v_cndmask_b32_e64 v98, v91, v181, s[24:25]
	v_cndmask_b32_e64 v97, v92, v181, s[26:27]
	v_cndmask_b32_e64 v96, v93, v181, s[28:29]
	v_cndmask_b32_e64 v95, v14, v181, s[30:31]
	v_cndmask_b32_e64 v94, v15, v181, s[34:35]
	s_mov_b64 s[38:39], 0

; __global__ void __launch_bounds__(512, 2) fwd_mega(Args a) {
	.amdhsa_kernel _Z8fwd_mega4Args
		.amdhsa_group_segment_fixed_size 0
		.amdhsa_private_segment_fixed_size 0
		.amdhsa_kernarg_size 408
		.amdhsa_user_sgpr_count 2
		.amdhsa_user_sgpr_dispatch_ptr 0
		.amdhsa_user_sgpr_queue_ptr 0
		.amdhsa_user_sgpr_kernarg_segment_ptr 1
		.amdhsa_user_sgpr_dispatch_id 0
		.amdhsa_user_sgpr_kernarg_preload_length 0
		.amdhsa_user_sgpr_kernarg_preload_offset 0
		.amdhsa_user_sgpr_private_segment_size 0
		.amdhsa_uses_dynamic_stack 0
		.amdhsa_enable_private_segment 0
		.amdhsa_system_sgpr_workgroup_id_x 1
		.amdhsa_system_sgpr_workgroup_id_y 0
		.amdhsa_system_sgpr_workgroup_id_z 0
		.amdhsa_system_sgpr_workgroup_info 0
		.amdhsa_system_vgpr_workitem_id 2
		.amdhsa_next_free_vgpr 246
		.amdhsa_next_free_sgpr 102
		.amdhsa_accum_offset 248
		.amdhsa_reserve_vcc 1
		.amdhsa_float_round_mode_32 0
		.amdhsa_float_round_mode_16_64 0
		.amdhsa_float_denorm_mode_32 3
		.amdhsa_float_denorm_mode_16_64 3
		.amdhsa_dx10_clamp 1
		.amdhsa_ieee_mode 1
		.amdhsa_fp16_overflow 0
		.amdhsa_tg_split 0
		.amdhsa_exception_fp_ieee_invalid_op 0
		.amdhsa_exception_fp_denorm_src 0
		.amdhsa_exception_fp_ieee_div_zero 0
		.amdhsa_exception_fp_ieee_overflow 0
		.amdhsa_exception_fp_ieee_underflow 0
		.amdhsa_exception_fp_ieee_inexact 0
		.amdhsa_exception_int_div_zero 0
	.end_amdhsa_kernel

; __global__ void __launch_bounds__(512, 2) fwd_mega(Args a) {
amdhsa.kernels:
  - .agpr_count:     0
    .args:
      - .offset:         0
        .size:           152
        .value_kind:     by_value
      - .offset:         152
        .size:           4
        .value_kind:     hidden_block_count_x
      - .offset:         156
        .size:           4
        .value_kind:     hidden_block_count_y
      - .offset:         160
        .size:           4
        .value_kind:     hidden_block_count_z
      - .offset:         164
        .size:           2
        .value_kind:     hidden_group_size_x
      - .offset:         166
        .size:           2
        .value_kind:     hidden_group_size_y
      - .offset:         168
        .size:           2
        .value_kind:     hidden_group_size_z
      - .offset:         170
        .size:           2
        .value_kind:     hidden_remainder_x
      - .offset:         172
        .size:           2
        .value_kind:     hidden_remainder_y
      - .offset:         174
        .size:           2
        .value_kind:     hidden_remainder_z
      - .offset:         192
        .size:           8
        .value_kind:     hidden_global_offset_x
      - .offset:         200
        .size:           8
        .value_kind:     hidden_global_offset_y
      - .offset:         208
        .size:           8
        .value_kind:     hidden_global_offset_z
      - .offset:         216
        .size:           2
        .value_kind:     hidden_grid_dims
      - .offset:         240
        .size:           8
        .value_kind:     hidden_multigrid_sync_arg
      - .offset:         272
        .size:           4
        .value_kind:     hidden_dynamic_lds_size
    .group_segment_fixed_size: 0
    .kernarg_segment_align: 8
    .kernarg_segment_size: 408
    .language:       OpenCL C
    .language_version:
      - 2
      - 0
    .max_flat_workgroup_size: 512
    .name:           _Z8fwd_mega4Args
    .private_segment_fixed_size: 0
    .sgpr_count:     108
    .sgpr_spill_count: 84
    .symbol:         _Z8fwd_mega4Args.kd
    .uniform_work_group_size: 1
    .uses_dynamic_stack: false
    .vgpr_count:     246
    .vgpr_spill_count: 0
    .wavefront_size: 64
